# RG-LRU chunk-local item copy-out: two batches of four LDS reads into four quads with counted waits (was eight serialized read/wait/store rounds)
# baseline (speedup 1.0000x reference)
.LBB0_439:
	s_or_b64 exec, exec, s[10:11]
	s_lshl_b32 s10, s21, 1
	s_or_b32 s10, s10, s18
	s_ashr_i32 s11, s10, 31
	s_lshl_b64 s[10:11], s[10:11], 15
	s_add_u32 s16, s96, s10
	s_addc_u32 s17, s97, s11
	s_and_b64 s[10:11], s[4:5], exec
	s_waitcnt lgkmcnt(0)
	s_barrier
	ds_read_b128 v[98:101], v148 offset:17408
	ds_read_b128 v[226:229], v148 offset:25600
	ds_read_b128 v[230:233], v148 offset:33792
	ds_read_b128 v[234:237], v148 offset:41984
	s_mov_b32 s10, 0xe080000
	s_cselect_b32 s10, 0xe8c0000, s10
	s_add_u32 s10, s16, s10
	s_addc_u32 s11, s17, 0
	s_and_b64 s[4:5], s[4:5], exec
	s_cselect_b32 s4, 0x12000000, s73
	s_add_u32 s4, s16, s4
	s_addc_u32 s5, s17, 0
	s_and_b64 vcc, exec, s[14:15]
	s_mov_b32 s16, s20
	v_lshl_add_u64 v[102:103], s[10:11], 0, v[110:111]
	s_waitcnt lgkmcnt(3)
	global_store_dwordx4 v[102:103], v[98:101], off
	v_lshl_add_u64 v[220:221], s[10:11], 0, v[114:115]
	s_waitcnt lgkmcnt(2)
	global_store_dwordx4 v[220:221], v[226:229], off
	v_lshl_add_u64 v[102:103], s[10:11], 0, v[116:117]
	s_waitcnt lgkmcnt(1)
	global_store_dwordx4 v[102:103], v[230:233], off
	v_lshl_add_u64 v[220:221], s[10:11], 0, v[118:119]
	s_waitcnt lgkmcnt(0)
	global_store_dwordx4 v[220:221], v[234:237], off
	ds_read_b128 v[98:101], v148 offset:50176
	ds_read_b128 v[226:229], v148 offset:58368
	ds_read_b128 v[230:233], v149 offset:16384
	ds_read_b128 v[234:237], v149 offset:24576
	v_lshl_add_u64 v[102:103], s[4:5], 0, v[110:111]
	s_waitcnt lgkmcnt(3)
	global_store_dwordx4 v[102:103], v[98:101], off
	v_lshl_add_u64 v[220:221], s[4:5], 0, v[114:115]
	s_waitcnt lgkmcnt(2)
	global_store_dwordx4 v[220:221], v[226:229], off
	v_lshl_add_u64 v[102:103], s[4:5], 0, v[116:117]
	s_waitcnt lgkmcnt(1)
	global_store_dwordx4 v[102:103], v[230:233], off
	v_lshl_add_u64 v[220:221], s[4:5], 0, v[118:119]
	s_waitcnt lgkmcnt(0)
	global_store_dwordx4 v[220:221], v[234:237], off
	s_cbranch_vccnz .LBB0_455
